# silupk: W_in SiLU epilogue variants regenerated with packed mul/add steps on 8 values (no serial chains, no hazard nops), on top of cumsumlds+ffwide+swapred
# baseline (speedup 1.0000x reference)
; __device__ __forceinline__ v4u pack8(const f32x4 a, const f32x4 b) { v4u w; w.x = cvt_pk_bf16(a[0], a[1]); w.y = cvt_pk_bf16(a[2], a[3]); w.z = cvt_pk_bf16(b[0], b[1]); w.w = cvt_pk_bf16(b[2], b[3]); return w; }
; __device__ __forceinline__ float silu_f(float x) { return x * __builtin_amdgcn_rcpf(1.f + __expf(-x)); }
;     __device__ __forceinline__ void operator()(const f32x4 (&acc)[2][2][4][2], const pg8::Unit& u, int wr, int wc, int fr, int fq) const {
;     ...
;         if (grp == 0) { WIN_LOOP( _Pragma("unroll") for (int i = 0; i < 4; ++i) { a[i] = silu_f(a[i]); b[i] = silu_f(b[i]); } *(v4u*)(QO + (size_t)row * DM + c) = pack8(a, b); ) }
;         else if (grp == 3) { WIN_LOOP( _Pragma("unroll") for (int i = 0; i < 4; ++i) { a[i] = silu_f(a[i]); b[i] = silu_f(b[i]); } *(v4u*)(GH + (size_t)row * 512 + c) = pack8(a, b); ) }
.LBB0_404:
	s_and_b64 vcc, exec, s[12:13]
	s_cbranch_vccz .LBB0_406
	v_readlane_b32 s12, v255, 39
	v_readlane_b32 s13, v255, 40
	v_lshlrev_b32_e32 v192, 1, v176
	v_mov_b32_e32 v188, 0xbfb8aa3b
	v_lshl_add_u32 v182, v166, 10, v192
	v_mov_b32_e32 v184, v250
	v_pk_mul_f32 v[128:129], v[60:61], v[184:185] op_sel_hi:[1,0]
	v_pk_mul_f32 v[130:131], v[62:63], v[184:185] op_sel_hi:[1,0]
	v_pk_mul_f32 v[132:133], v[56:57], v[184:185] op_sel_hi:[1,0]
	v_pk_mul_f32 v[134:135], v[58:59], v[184:185] op_sel_hi:[1,0]
	v_pk_mul_f32 v[136:137], v[128:129], v[188:189] op_sel_hi:[1,0]
	v_pk_mul_f32 v[138:139], v[130:131], v[188:189] op_sel_hi:[1,0]
	v_pk_mul_f32 v[140:141], v[132:133], v[188:189] op_sel_hi:[1,0]
	v_pk_mul_f32 v[142:143], v[134:135], v[188:189] op_sel_hi:[1,0]
	v_exp_f32_e32 v136, v136
	v_exp_f32_e32 v137, v137
	v_exp_f32_e32 v138, v138
	v_exp_f32_e32 v139, v139
	v_exp_f32_e32 v140, v140
	v_exp_f32_e32 v141, v141
	v_exp_f32_e32 v142, v142
	v_exp_f32_e32 v143, v143
	v_pk_add_f32 v[136:137], v[136:137], 1.0 op_sel_hi:[1,0]
	v_pk_add_f32 v[138:139], v[138:139], 1.0 op_sel_hi:[1,0]
	v_pk_add_f32 v[140:141], v[140:141], 1.0 op_sel_hi:[1,0]
	v_pk_add_f32 v[142:143], v[142:143], 1.0 op_sel_hi:[1,0]
	v_rcp_f32_e32 v136, v136
	v_rcp_f32_e32 v137, v137
	v_rcp_f32_e32 v138, v138
	v_rcp_f32_e32 v139, v139
	v_rcp_f32_e32 v140, v140
	v_rcp_f32_e32 v141, v141
	v_rcp_f32_e32 v142, v142
	v_rcp_f32_e32 v143, v143
	v_pk_mul_f32 v[136:137], v[128:129], v[136:137]
	v_pk_mul_f32 v[138:139], v[130:131], v[138:139]
	v_pk_mul_f32 v[140:141], v[132:133], v[140:141]
	v_pk_mul_f32 v[142:143], v[134:135], v[142:143]
	v_cvt_pk_bf16_f32 v144, v136, v137
	v_cvt_pk_bf16_f32 v145, v138, v139
	v_cvt_pk_bf16_f32 v146, v140, v141
	v_cvt_pk_bf16_f32 v147, v142, v143
	global_store_dwordx4 v182, v[144:147], s[12:13]
	v_pk_mul_f32 v[128:129], v[124:125], v[184:185] op_sel_hi:[1,0]
	v_pk_mul_f32 v[130:131], v[126:127], v[184:185] op_sel_hi:[1,0]
	v_pk_mul_f32 v[132:133], v[120:121], v[184:185] op_sel_hi:[1,0]
	v_pk_mul_f32 v[134:135], v[122:123], v[184:185] op_sel_hi:[1,0]
	v_pk_mul_f32 v[136:137], v[128:129], v[188:189] op_sel_hi:[1,0]
	v_pk_mul_f32 v[138:139], v[130:131], v[188:189] op_sel_hi:[1,0]
	v_pk_mul_f32 v[140:141], v[132:133], v[188:189] op_sel_hi:[1,0]
	v_pk_mul_f32 v[142:143], v[134:135], v[188:189] op_sel_hi:[1,0]
	v_exp_f32_e32 v136, v136
	v_exp_f32_e32 v137, v137
	v_exp_f32_e32 v138, v138
	v_exp_f32_e32 v139, v139
	v_exp_f32_e32 v140, v140
	v_exp_f32_e32 v141, v141
	v_exp_f32_e32 v142, v142
	v_exp_f32_e32 v143, v143
	v_pk_add_f32 v[136:137], v[136:137], 1.0 op_sel_hi:[1,0]
	v_pk_add_f32 v[138:139], v[138:139], 1.0 op_sel_hi:[1,0]
	v_pk_add_f32 v[140:141], v[140:141], 1.0 op_sel_hi:[1,0]
	v_pk_add_f32 v[142:143], v[142:143], 1.0 op_sel_hi:[1,0]
	v_rcp_f32_e32 v136, v136
	v_rcp_f32_e32 v137, v137
	v_rcp_f32_e32 v138, v138
	v_rcp_f32_e32 v139, v139
	v_rcp_f32_e32 v140, v140
	v_rcp_f32_e32 v141, v141
	v_rcp_f32_e32 v142, v142
	v_rcp_f32_e32 v143, v143
	v_pk_mul_f32 v[136:137], v[128:129], v[136:137]
	v_pk_mul_f32 v[138:139], v[130:131], v[138:139]
	v_pk_mul_f32 v[140:141], v[132:133], v[140:141]
	v_pk_mul_f32 v[142:143], v[134:135], v[142:143]
	v_cvt_pk_bf16_f32 v148, v136, v137
	v_cvt_pk_bf16_f32 v149, v138, v139
	v_cvt_pk_bf16_f32 v150, v140, v141
	v_cvt_pk_bf16_f32 v151, v142, v143
	global_store_dwordx4 v182, v[148:151], s[12:13] offset:256
	v_add_u32_e32 v181, 16, v166
	v_lshl_add_u32 v183, v181, 10, v192
	v_mov_b32_e32 v186, v251
	v_pk_mul_f32 v[128:129], v[52:53], v[186:187] op_sel_hi:[1,0]
	v_pk_mul_f32 v[130:131], v[54:55], v[186:187] op_sel_hi:[1,0]
	v_pk_mul_f32 v[132:133], v[48:49], v[186:187] op_sel_hi:[1,0]
	v_pk_mul_f32 v[134:135], v[50:51], v[186:187] op_sel_hi:[1,0]
	v_pk_mul_f32 v[136:137], v[128:129], v[188:189] op_sel_hi:[1,0]
	v_pk_mul_f32 v[138:139], v[130:131], v[188:189] op_sel_hi:[1,0]
	v_pk_mul_f32 v[140:141], v[132:133], v[188:189] op_sel_hi:[1,0]
	v_pk_mul_f32 v[142:143], v[134:135], v[188:189] op_sel_hi:[1,0]
	v_exp_f32_e32 v136, v136
	v_exp_f32_e32 v137, v137
	v_exp_f32_e32 v138, v138
	v_exp_f32_e32 v139, v139
	v_exp_f32_e32 v140, v140
	v_exp_f32_e32 v141, v141
	v_exp_f32_e32 v142, v142
	v_exp_f32_e32 v143, v143
	v_pk_add_f32 v[136:137], v[136:137], 1.0 op_sel_hi:[1,0]
	v_pk_add_f32 v[138:139], v[138:139], 1.0 op_sel_hi:[1,0]
	v_pk_add_f32 v[140:141], v[140:141], 1.0 op_sel_hi:[1,0]
	v_pk_add_f32 v[142:143], v[142:143], 1.0 op_sel_hi:[1,0]
	v_rcp_f32_e32 v136, v136
	v_rcp_f32_e32 v137, v137
	v_rcp_f32_e32 v138, v138
	v_rcp_f32_e32 v139, v139
	v_rcp_f32_e32 v140, v140
	v_rcp_f32_e32 v141, v141
	v_rcp_f32_e32 v142, v142
	v_rcp_f32_e32 v143, v143
	v_pk_mul_f32 v[136:137], v[128:129], v[136:137]
	v_pk_mul_f32 v[138:139], v[130:131], v[138:139]
	v_pk_mul_f32 v[140:141], v[132:133], v[140:141]
	v_pk_mul_f32 v[142:143], v[134:135], v[142:143]
	v_cvt_pk_bf16_f32 v144, v136, v137
	v_cvt_pk_bf16_f32 v145, v138, v139
	v_cvt_pk_bf16_f32 v146, v140, v141
	v_cvt_pk_bf16_f32 v147, v142, v143
	global_store_dwordx4 v183, v[144:147], s[12:13]
	v_pk_mul_f32 v[128:129], v[116:117], v[186:187] op_sel_hi:[1,0]
	v_pk_mul_f32 v[130:131], v[118:119], v[186:187] op_sel_hi:[1,0]
	v_pk_mul_f32 v[132:133], v[112:113], v[186:187] op_sel_hi:[1,0]
	v_pk_mul_f32 v[134:135], v[114:115], v[186:187] op_sel_hi:[1,0]
	v_pk_mul_f32 v[136:137], v[128:129], v[188:189] op_sel_hi:[1,0]
	v_pk_mul_f32 v[138:139], v[130:131], v[188:189] op_sel_hi:[1,0]
	v_pk_mul_f32 v[140:141], v[132:133], v[188:189] op_sel_hi:[1,0]
	v_pk_mul_f32 v[142:143], v[134:135], v[188:189] op_sel_hi:[1,0]
	v_exp_f32_e32 v136, v136
	v_exp_f32_e32 v137, v137
	v_exp_f32_e32 v138, v138
	v_exp_f32_e32 v139, v139
; __device__ __forceinline__ v4u pack8(const f32x4 a, const f32x4 b) { v4u w; w.x = cvt_pk_bf16(a[0], a[1]); w.y = cvt_pk_bf16(a[2], a[3]); w.z = cvt_pk_bf16(b[0], b[1]); w.w = cvt_pk_bf16(b[2], b[3]); return w; }
; __device__ __forceinline__ float silu_f(float x) { return x * __builtin_amdgcn_rcpf(1.f + __expf(-x)); }
;     __device__ __forceinline__ void operator()(const f32x4 (&acc)[2][2][4][2], const pg8::Unit& u, int wr, int wc, int fr, int fq) const {
;     ...
;         if (grp == 0) { WIN_LOOP( _Pragma("unroll") for (int i = 0; i < 4; ++i) { a[i] = silu_f(a[i]); b[i] = silu_f(b[i]); } *(v4u*)(QO + (size_t)row * DM + c) = pack8(a, b); ) }
;         else if (grp == 3) { WIN_LOOP( _Pragma("unroll") for (int i = 0; i < 4; ++i) { a[i] = silu_f(a[i]); b[i] = silu_f(b[i]); } *(v4u*)(GH + (size_t)row * 512 + c) = pack8(a, b); ) }
	v_exp_f32_e32 v140, v140
	v_exp_f32_e32 v141, v141
	v_exp_f32_e32 v142, v142
	v_exp_f32_e32 v143, v143
	v_pk_add_f32 v[136:137], v[136:137], 1.0 op_sel_hi:[1,0]
	v_pk_add_f32 v[138:139], v[138:139], 1.0 op_sel_hi:[1,0]
	v_pk_add_f32 v[140:141], v[140:141], 1.0 op_sel_hi:[1,0]
	v_pk_add_f32 v[142:143], v[142:143], 1.0 op_sel_hi:[1,0]
	v_rcp_f32_e32 v136, v136
	v_rcp_f32_e32 v137, v137
	v_rcp_f32_e32 v138, v138
	v_rcp_f32_e32 v139, v139
	v_rcp_f32_e32 v140, v140
	v_rcp_f32_e32 v141, v141
	v_rcp_f32_e32 v142, v142
	v_rcp_f32_e32 v143, v143
	v_pk_mul_f32 v[136:137], v[128:129], v[136:137]
	v_pk_mul_f32 v[138:139], v[130:131], v[138:139]
	v_pk_mul_f32 v[140:141], v[132:133], v[140:141]
	v_pk_mul_f32 v[142:143], v[134:135], v[142:143]
	v_cvt_pk_bf16_f32 v148, v136, v137
	v_cvt_pk_bf16_f32 v149, v138, v139
	v_cvt_pk_bf16_f32 v150, v140, v141
	v_cvt_pk_bf16_f32 v151, v142, v143
	global_store_dwordx4 v183, v[148:151], s[12:13] offset:256
	v_add_u32_e32 v180, 32, v166
	v_lshl_add_u32 v182, v180, 10, v192
	v_mov_b32_e32 v184, v252
	v_pk_mul_f32 v[128:129], v[44:45], v[184:185] op_sel_hi:[1,0]
	v_pk_mul_f32 v[130:131], v[46:47], v[184:185] op_sel_hi:[1,0]
	v_pk_mul_f32 v[132:133], v[40:41], v[184:185] op_sel_hi:[1,0]
	v_pk_mul_f32 v[134:135], v[42:43], v[184:185] op_sel_hi:[1,0]
	v_pk_mul_f32 v[136:137], v[128:129], v[188:189] op_sel_hi:[1,0]
	v_pk_mul_f32 v[138:139], v[130:131], v[188:189] op_sel_hi:[1,0]
	v_pk_mul_f32 v[140:141], v[132:133], v[188:189] op_sel_hi:[1,0]
	v_pk_mul_f32 v[142:143], v[134:135], v[188:189] op_sel_hi:[1,0]
	v_exp_f32_e32 v136, v136
	v_exp_f32_e32 v137, v137
	v_exp_f32_e32 v138, v138
	v_exp_f32_e32 v139, v139
	v_exp_f32_e32 v140, v140
	v_exp_f32_e32 v141, v141
	v_exp_f32_e32 v142, v142
	v_exp_f32_e32 v143, v143
	v_pk_add_f32 v[136:137], v[136:137], 1.0 op_sel_hi:[1,0]
	v_pk_add_f32 v[138:139], v[138:139], 1.0 op_sel_hi:[1,0]
	v_pk_add_f32 v[140:141], v[140:141], 1.0 op_sel_hi:[1,0]
	v_pk_add_f32 v[142:143], v[142:143], 1.0 op_sel_hi:[1,0]
	v_rcp_f32_e32 v136, v136
	v_rcp_f32_e32 v137, v137
	v_rcp_f32_e32 v138, v138
	v_rcp_f32_e32 v139, v139
	v_rcp_f32_e32 v140, v140
	v_rcp_f32_e32 v141, v141
	v_rcp_f32_e32 v142, v142
	v_rcp_f32_e32 v143, v143
	v_pk_mul_f32 v[136:137], v[128:129], v[136:137]
	v_pk_mul_f32 v[138:139], v[130:131], v[138:139]
	v_pk_mul_f32 v[140:141], v[132:133], v[140:141]
	v_pk_mul_f32 v[142:143], v[134:135], v[142:143]
	v_cvt_pk_bf16_f32 v144, v136, v137
	v_cvt_pk_bf16_f32 v145, v138, v139
	v_cvt_pk_bf16_f32 v146, v140, v141
	v_cvt_pk_bf16_f32 v147, v142, v143
	global_store_dwordx4 v182, v[144:147], s[12:13]
	v_pk_mul_f32 v[128:129], v[108:109], v[184:185] op_sel_hi:[1,0]
	v_pk_mul_f32 v[130:131], v[110:111], v[184:185] op_sel_hi:[1,0]
	v_pk_mul_f32 v[132:133], v[104:105], v[184:185] op_sel_hi:[1,0]
	v_pk_mul_f32 v[134:135], v[106:107], v[184:185] op_sel_hi:[1,0]
	v_pk_mul_f32 v[136:137], v[128:129], v[188:189] op_sel_hi:[1,0]
	v_pk_mul_f32 v[138:139], v[130:131], v[188:189] op_sel_hi:[1,0]
	v_pk_mul_f32 v[140:141], v[132:133], v[188:189] op_sel_hi:[1,0]
	v_pk_mul_f32 v[142:143], v[134:135], v[188:189] op_sel_hi:[1,0]
	v_exp_f32_e32 v136, v136
	v_exp_f32_e32 v137, v137
	v_exp_f32_e32 v138, v138
	v_exp_f32_e32 v139, v139
	v_exp_f32_e32 v140, v140
	v_exp_f32_e32 v141, v141
	v_exp_f32_e32 v142, v142
	v_exp_f32_e32 v143, v143
	v_pk_add_f32 v[136:137], v[136:137], 1.0 op_sel_hi:[1,0]
	v_pk_add_f32 v[138:139], v[138:139], 1.0 op_sel_hi:[1,0]
	v_pk_add_f32 v[140:141], v[140:141], 1.0 op_sel_hi:[1,0]
	v_pk_add_f32 v[142:143], v[142:143], 1.0 op_sel_hi:[1,0]
	v_rcp_f32_e32 v136, v136
	v_rcp_f32_e32 v137, v137
	v_rcp_f32_e32 v138, v138
	v_rcp_f32_e32 v139, v139
	v_rcp_f32_e32 v140, v140
	v_rcp_f32_e32 v141, v141
	v_rcp_f32_e32 v142, v142
	v_rcp_f32_e32 v143, v143
	v_pk_mul_f32 v[136:137], v[128:129], v[136:137]
	v_pk_mul_f32 v[138:139], v[130:131], v[138:139]
	v_pk_mul_f32 v[140:141], v[132:133], v[140:141]
	v_pk_mul_f32 v[142:143], v[134:135], v[142:143]
	v_cvt_pk_bf16_f32 v148, v136, v137
	v_cvt_pk_bf16_f32 v149, v138, v139
	v_cvt_pk_bf16_f32 v150, v140, v141
	v_cvt_pk_bf16_f32 v151, v142, v143
	global_store_dwordx4 v182, v[148:151], s[12:13] offset:256
	v_add_u32_e32 v181, 48, v166
	v_lshl_add_u32 v183, v181, 10, v192
	v_mov_b32_e32 v186, v253
	v_pk_mul_f32 v[128:129], v[36:37], v[186:187] op_sel_hi:[1,0]
	v_pk_mul_f32 v[130:131], v[38:39], v[186:187] op_sel_hi:[1,0]
	v_pk_mul_f32 v[132:133], v[32:33], v[186:187] op_sel_hi:[1,0]
	v_pk_mul_f32 v[134:135], v[34:35], v[186:187] op_sel_hi:[1,0]
	v_pk_mul_f32 v[136:137], v[128:129], v[188:189] op_sel_hi:[1,0]
	v_pk_mul_f32 v[138:139], v[130:131], v[188:189] op_sel_hi:[1,0]
	v_pk_mul_f32 v[140:141], v[132:133], v[188:189] op_sel_hi:[1,0]
	v_pk_mul_f32 v[142:143], v[134:135], v[188:189] op_sel_hi:[1,0]
	v_exp_f32_e32 v136, v136
	v_exp_f32_e32 v137, v137
	v_exp_f32_e32 v138, v138
	v_exp_f32_e32 v139, v139
	v_exp_f32_e32 v140, v140
	v_exp_f32_e32 v141, v141
	v_exp_f32_e32 v142, v142
	v_exp_f32_e32 v143, v143
	v_pk_add_f32 v[136:137], v[136:137], 1.0 op_sel_hi:[1,0]
	v_pk_add_f32 v[138:139], v[138:139], 1.0 op_sel_hi:[1,0]
	v_pk_add_f32 v[140:141], v[140:141], 1.0 op_sel_hi:[1,0]
	v_pk_add_f32 v[142:143], v[142:143], 1.0 op_sel_hi:[1,0]
	v_rcp_f32_e32 v136, v136
	v_rcp_f32_e32 v137, v137
	v_rcp_f32_e32 v138, v138
	v_rcp_f32_e32 v139, v139
	v_rcp_f32_e32 v140, v140
	v_rcp_f32_e32 v141, v141
	v_rcp_f32_e32 v142, v142
	v_rcp_f32_e32 v143, v143
	v_pk_mul_f32 v[136:137], v[128:129], v[136:137]
	v_pk_mul_f32 v[138:139], v[130:131], v[138:139]
	v_pk_mul_f32 v[140:141], v[132:133], v[140:141]
	v_pk_mul_f32 v[142:143], v[134:135], v[142:143]
	v_cvt_pk_bf16_f32 v144, v136, v137
; __device__ __forceinline__ v4u pack8(const f32x4 a, const f32x4 b) { v4u w; w.x = cvt_pk_bf16(a[0], a[1]); w.y = cvt_pk_bf16(a[2], a[3]); w.z = cvt_pk_bf16(b[0], b[1]); w.w = cvt_pk_bf16(b[2], b[3]); return w; }
; __device__ __forceinline__ float silu_f(float x) { return x * __builtin_amdgcn_rcpf(1.f + __expf(-x)); }
;     __device__ __forceinline__ void operator()(const f32x4 (&acc)[2][2][4][2], const pg8::Unit& u, int wr, int wc, int fr, int fq) const {
;     ...
;         if (grp == 0) { WIN_LOOP( _Pragma("unroll") for (int i = 0; i < 4; ++i) { a[i] = silu_f(a[i]); b[i] = silu_f(b[i]); } *(v4u*)(QO + (size_t)row * DM + c) = pack8(a, b); ) }
;         else if (grp == 3) { WIN_LOOP( _Pragma("unroll") for (int i = 0; i < 4; ++i) { a[i] = silu_f(a[i]); b[i] = silu_f(b[i]); } *(v4u*)(GH + (size_t)row * 512 + c) = pack8(a, b); ) }
	v_cvt_pk_bf16_f32 v145, v138, v139
	v_cvt_pk_bf16_f32 v146, v140, v141
	v_cvt_pk_bf16_f32 v147, v142, v143
	global_store_dwordx4 v183, v[144:147], s[12:13]
	v_pk_mul_f32 v[128:129], v[100:101], v[186:187] op_sel_hi:[1,0]
	v_pk_mul_f32 v[130:131], v[102:103], v[186:187] op_sel_hi:[1,0]
	v_pk_mul_f32 v[132:133], v[96:97], v[186:187] op_sel_hi:[1,0]
	v_pk_mul_f32 v[134:135], v[98:99], v[186:187] op_sel_hi:[1,0]
	v_pk_mul_f32 v[136:137], v[128:129], v[188:189] op_sel_hi:[1,0]
	v_pk_mul_f32 v[138:139], v[130:131], v[188:189] op_sel_hi:[1,0]
	v_pk_mul_f32 v[140:141], v[132:133], v[188:189] op_sel_hi:[1,0]
	v_pk_mul_f32 v[142:143], v[134:135], v[188:189] op_sel_hi:[1,0]
	v_exp_f32_e32 v136, v136
	v_exp_f32_e32 v137, v137
	v_exp_f32_e32 v138, v138
	v_exp_f32_e32 v139, v139
	v_exp_f32_e32 v140, v140
	v_exp_f32_e32 v141, v141
	v_exp_f32_e32 v142, v142
	v_exp_f32_e32 v143, v143
	v_pk_add_f32 v[136:137], v[136:137], 1.0 op_sel_hi:[1,0]
	v_pk_add_f32 v[138:139], v[138:139], 1.0 op_sel_hi:[1,0]
	v_pk_add_f32 v[140:141], v[140:141], 1.0 op_sel_hi:[1,0]
	v_pk_add_f32 v[142:143], v[142:143], 1.0 op_sel_hi:[1,0]
	v_rcp_f32_e32 v136, v136
	v_rcp_f32_e32 v137, v137
	v_rcp_f32_e32 v138, v138
	v_rcp_f32_e32 v139, v139
	v_rcp_f32_e32 v140, v140
	v_rcp_f32_e32 v141, v141
	v_rcp_f32_e32 v142, v142
	v_rcp_f32_e32 v143, v143
	v_pk_mul_f32 v[136:137], v[128:129], v[136:137]
	v_pk_mul_f32 v[138:139], v[130:131], v[138:139]
	v_pk_mul_f32 v[140:141], v[132:133], v[140:141]
	v_pk_mul_f32 v[142:143], v[134:135], v[142:143]
	v_cvt_pk_bf16_f32 v148, v136, v137
	v_cvt_pk_bf16_f32 v149, v138, v139
	v_cvt_pk_bf16_f32 v150, v140, v141
	v_cvt_pk_bf16_f32 v151, v142, v143
	global_store_dwordx4 v183, v[148:151], s[12:13] offset:256
	v_add_u32_e32 v180, 128, v166
	v_lshl_add_u32 v182, v180, 10, v192
	v_mov_b32_e32 v184, v254
	v_pk_mul_f32 v[128:129], v[28:29], v[184:185] op_sel_hi:[1,0]
	v_pk_mul_f32 v[130:131], v[30:31], v[184:185] op_sel_hi:[1,0]
	v_pk_mul_f32 v[132:133], v[24:25], v[184:185] op_sel_hi:[1,0]
	v_pk_mul_f32 v[134:135], v[26:27], v[184:185] op_sel_hi:[1,0]
	v_pk_mul_f32 v[136:137], v[128:129], v[188:189] op_sel_hi:[1,0]
	v_pk_mul_f32 v[138:139], v[130:131], v[188:189] op_sel_hi:[1,0]
	v_pk_mul_f32 v[140:141], v[132:133], v[188:189] op_sel_hi:[1,0]
	v_pk_mul_f32 v[142:143], v[134:135], v[188:189] op_sel_hi:[1,0]
	v_exp_f32_e32 v136, v136
	v_exp_f32_e32 v137, v137
	v_exp_f32_e32 v138, v138
	v_exp_f32_e32 v139, v139
	v_exp_f32_e32 v140, v140
	v_exp_f32_e32 v141, v141
	v_exp_f32_e32 v142, v142
	v_exp_f32_e32 v143, v143
	v_pk_add_f32 v[136:137], v[136:137], 1.0 op_sel_hi:[1,0]
	v_pk_add_f32 v[138:139], v[138:139], 1.0 op_sel_hi:[1,0]
	v_pk_add_f32 v[140:141], v[140:141], 1.0 op_sel_hi:[1,0]
	v_pk_add_f32 v[142:143], v[142:143], 1.0 op_sel_hi:[1,0]
	v_rcp_f32_e32 v136, v136
	v_rcp_f32_e32 v137, v137
	v_rcp_f32_e32 v138, v138
	v_rcp_f32_e32 v139, v139
	v_rcp_f32_e32 v140, v140
	v_rcp_f32_e32 v141, v141
	v_rcp_f32_e32 v142, v142
	v_rcp_f32_e32 v143, v143
	v_pk_mul_f32 v[136:137], v[128:129], v[136:137]
	v_pk_mul_f32 v[138:139], v[130:131], v[138:139]
	v_pk_mul_f32 v[140:141], v[132:133], v[140:141]
	v_pk_mul_f32 v[142:143], v[134:135], v[142:143]
	v_cvt_pk_bf16_f32 v144, v136, v137
	v_cvt_pk_bf16_f32 v145, v138, v139
	v_cvt_pk_bf16_f32 v146, v140, v141
	v_cvt_pk_bf16_f32 v147, v142, v143
	global_store_dwordx4 v182, v[144:147], s[12:13]
	v_pk_mul_f32 v[128:129], v[92:93], v[184:185] op_sel_hi:[1,0]
	v_pk_mul_f32 v[130:131], v[94:95], v[184:185] op_sel_hi:[1,0]
	v_pk_mul_f32 v[132:133], v[88:89], v[184:185] op_sel_hi:[1,0]
	v_pk_mul_f32 v[134:135], v[90:91], v[184:185] op_sel_hi:[1,0]
	v_pk_mul_f32 v[136:137], v[128:129], v[188:189] op_sel_hi:[1,0]
	v_pk_mul_f32 v[138:139], v[130:131], v[188:189] op_sel_hi:[1,0]
	v_pk_mul_f32 v[140:141], v[132:133], v[188:189] op_sel_hi:[1,0]
	v_pk_mul_f32 v[142:143], v[134:135], v[188:189] op_sel_hi:[1,0]
	v_exp_f32_e32 v136, v136
	v_exp_f32_e32 v137, v137
	v_exp_f32_e32 v138, v138
	v_exp_f32_e32 v139, v139
	v_exp_f32_e32 v140, v140
	v_exp_f32_e32 v141, v141
	v_exp_f32_e32 v142, v142
	v_exp_f32_e32 v143, v143
	v_pk_add_f32 v[136:137], v[136:137], 1.0 op_sel_hi:[1,0]
	v_pk_add_f32 v[138:139], v[138:139], 1.0 op_sel_hi:[1,0]
	v_pk_add_f32 v[140:141], v[140:141], 1.0 op_sel_hi:[1,0]
	v_pk_add_f32 v[142:143], v[142:143], 1.0 op_sel_hi:[1,0]
	v_rcp_f32_e32 v136, v136
	v_rcp_f32_e32 v137, v137
	v_rcp_f32_e32 v138, v138
	v_rcp_f32_e32 v139, v139
	v_rcp_f32_e32 v140, v140
	v_rcp_f32_e32 v141, v141
	v_rcp_f32_e32 v142, v142
	v_rcp_f32_e32 v143, v143
	v_pk_mul_f32 v[136:137], v[128:129], v[136:137]
	v_pk_mul_f32 v[138:139], v[130:131], v[138:139]
	v_pk_mul_f32 v[140:141], v[132:133], v[140:141]
	v_pk_mul_f32 v[142:143], v[134:135], v[142:143]
	v_cvt_pk_bf16_f32 v148, v136, v137
	v_cvt_pk_bf16_f32 v149, v138, v139
	v_cvt_pk_bf16_f32 v150, v140, v141
	v_cvt_pk_bf16_f32 v151, v142, v143
	global_store_dwordx4 v182, v[148:151], s[12:13] offset:256
	v_add_u32_e32 v181, 144, v166
	v_lshl_add_u32 v183, v181, 10, v192
	v_mov_b32_e32 v186, v240
	v_pk_mul_f32 v[128:129], v[20:21], v[186:187] op_sel_hi:[1,0]
	v_pk_mul_f32 v[130:131], v[22:23], v[186:187] op_sel_hi:[1,0]
	v_pk_mul_f32 v[132:133], v[16:17], v[186:187] op_sel_hi:[1,0]
	v_pk_mul_f32 v[134:135], v[18:19], v[186:187] op_sel_hi:[1,0]
	v_pk_mul_f32 v[136:137], v[128:129], v[188:189] op_sel_hi:[1,0]
	v_pk_mul_f32 v[138:139], v[130:131], v[188:189] op_sel_hi:[1,0]
	v_pk_mul_f32 v[140:141], v[132:133], v[188:189] op_sel_hi:[1,0]
	v_pk_mul_f32 v[142:143], v[134:135], v[188:189] op_sel_hi:[1,0]
	v_exp_f32_e32 v136, v136
	v_exp_f32_e32 v137, v137
	v_exp_f32_e32 v138, v138
	v_exp_f32_e32 v139, v139
; __device__ __forceinline__ v4u pack8(const f32x4 a, const f32x4 b) { v4u w; w.x = cvt_pk_bf16(a[0], a[1]); w.y = cvt_pk_bf16(a[2], a[3]); w.z = cvt_pk_bf16(b[0], b[1]); w.w = cvt_pk_bf16(b[2], b[3]); return w; }
; __device__ __forceinline__ float silu_f(float x) { return x * __builtin_amdgcn_rcpf(1.f + __expf(-x)); }
;     __device__ __forceinline__ void operator()(const f32x4 (&acc)[2][2][4][2], const pg8::Unit& u, int wr, int wc, int fr, int fq) const {
;     ...
;         if (grp == 0) { WIN_LOOP( _Pragma("unroll") for (int i = 0; i < 4; ++i) { a[i] = silu_f(a[i]); b[i] = silu_f(b[i]); } *(v4u*)(QO + (size_t)row * DM + c) = pack8(a, b); ) }
;         else if (grp == 3) { WIN_LOOP( _Pragma("unroll") for (int i = 0; i < 4; ++i) { a[i] = silu_f(a[i]); b[i] = silu_f(b[i]); } *(v4u*)(GH + (size_t)row * 512 + c) = pack8(a, b); ) }
	v_exp_f32_e32 v140, v140
	v_exp_f32_e32 v141, v141
	v_exp_f32_e32 v142, v142
	v_exp_f32_e32 v143, v143
	v_pk_add_f32 v[136:137], v[136:137], 1.0 op_sel_hi:[1,0]
	v_pk_add_f32 v[138:139], v[138:139], 1.0 op_sel_hi:[1,0]
	v_pk_add_f32 v[140:141], v[140:141], 1.0 op_sel_hi:[1,0]
	v_pk_add_f32 v[142:143], v[142:143], 1.0 op_sel_hi:[1,0]
	v_rcp_f32_e32 v136, v136
	v_rcp_f32_e32 v137, v137
	v_rcp_f32_e32 v138, v138
	v_rcp_f32_e32 v139, v139
	v_rcp_f32_e32 v140, v140
	v_rcp_f32_e32 v141, v141
	v_rcp_f32_e32 v142, v142
	v_rcp_f32_e32 v143, v143
	v_pk_mul_f32 v[136:137], v[128:129], v[136:137]
	v_pk_mul_f32 v[138:139], v[130:131], v[138:139]
	v_pk_mul_f32 v[140:141], v[132:133], v[140:141]
	v_pk_mul_f32 v[142:143], v[134:135], v[142:143]
	v_cvt_pk_bf16_f32 v144, v136, v137
	v_cvt_pk_bf16_f32 v145, v138, v139
	v_cvt_pk_bf16_f32 v146, v140, v141
	v_cvt_pk_bf16_f32 v147, v142, v143
	global_store_dwordx4 v183, v[144:147], s[12:13]
	v_pk_mul_f32 v[128:129], v[84:85], v[186:187] op_sel_hi:[1,0]
	v_pk_mul_f32 v[130:131], v[86:87], v[186:187] op_sel_hi:[1,0]
	v_pk_mul_f32 v[132:133], v[80:81], v[186:187] op_sel_hi:[1,0]
	v_pk_mul_f32 v[134:135], v[82:83], v[186:187] op_sel_hi:[1,0]
	v_pk_mul_f32 v[136:137], v[128:129], v[188:189] op_sel_hi:[1,0]
	v_pk_mul_f32 v[138:139], v[130:131], v[188:189] op_sel_hi:[1,0]
	v_pk_mul_f32 v[140:141], v[132:133], v[188:189] op_sel_hi:[1,0]
	v_pk_mul_f32 v[142:143], v[134:135], v[188:189] op_sel_hi:[1,0]
	v_exp_f32_e32 v136, v136
	v_exp_f32_e32 v137, v137
	v_exp_f32_e32 v138, v138
	v_exp_f32_e32 v139, v139
	v_exp_f32_e32 v140, v140
	v_exp_f32_e32 v141, v141
	v_exp_f32_e32 v142, v142
	v_exp_f32_e32 v143, v143
	v_pk_add_f32 v[136:137], v[136:137], 1.0 op_sel_hi:[1,0]
	v_pk_add_f32 v[138:139], v[138:139], 1.0 op_sel_hi:[1,0]
	v_pk_add_f32 v[140:141], v[140:141], 1.0 op_sel_hi:[1,0]
	v_pk_add_f32 v[142:143], v[142:143], 1.0 op_sel_hi:[1,0]
	v_rcp_f32_e32 v136, v136
	v_rcp_f32_e32 v137, v137
	v_rcp_f32_e32 v138, v138
	v_rcp_f32_e32 v139, v139
	v_rcp_f32_e32 v140, v140
	v_rcp_f32_e32 v141, v141
	v_rcp_f32_e32 v142, v142
	v_rcp_f32_e32 v143, v143
	v_pk_mul_f32 v[136:137], v[128:129], v[136:137]
	v_pk_mul_f32 v[138:139], v[130:131], v[138:139]
	v_pk_mul_f32 v[140:141], v[132:133], v[140:141]
	v_pk_mul_f32 v[142:143], v[134:135], v[142:143]
	v_cvt_pk_bf16_f32 v148, v136, v137
	v_cvt_pk_bf16_f32 v149, v138, v139
	v_cvt_pk_bf16_f32 v150, v140, v141
	v_cvt_pk_bf16_f32 v151, v142, v143
	global_store_dwordx4 v183, v[148:151], s[12:13] offset:256
	v_add_u32_e32 v180, 160, v166
	v_lshl_add_u32 v182, v180, 10, v192
	v_mov_b32_e32 v184, v241
	v_pk_mul_f32 v[128:129], v[12:13], v[184:185] op_sel_hi:[1,0]
	v_pk_mul_f32 v[130:131], v[14:15], v[184:185] op_sel_hi:[1,0]
	v_pk_mul_f32 v[132:133], v[8:9], v[184:185] op_sel_hi:[1,0]
	v_pk_mul_f32 v[134:135], v[10:11], v[184:185] op_sel_hi:[1,0]
	v_pk_mul_f32 v[136:137], v[128:129], v[188:189] op_sel_hi:[1,0]
	v_pk_mul_f32 v[138:139], v[130:131], v[188:189] op_sel_hi:[1,0]
	v_pk_mul_f32 v[140:141], v[132:133], v[188:189] op_sel_hi:[1,0]
	v_pk_mul_f32 v[142:143], v[134:135], v[188:189] op_sel_hi:[1,0]
	v_exp_f32_e32 v136, v136
	v_exp_f32_e32 v137, v137
	v_exp_f32_e32 v138, v138
	v_exp_f32_e32 v139, v139
	v_exp_f32_e32 v140, v140
	v_exp_f32_e32 v141, v141
	v_exp_f32_e32 v142, v142
	v_exp_f32_e32 v143, v143
	v_pk_add_f32 v[136:137], v[136:137], 1.0 op_sel_hi:[1,0]
	v_pk_add_f32 v[138:139], v[138:139], 1.0 op_sel_hi:[1,0]
	v_pk_add_f32 v[140:141], v[140:141], 1.0 op_sel_hi:[1,0]
	v_pk_add_f32 v[142:143], v[142:143], 1.0 op_sel_hi:[1,0]
	v_rcp_f32_e32 v136, v136
	v_rcp_f32_e32 v137, v137
	v_rcp_f32_e32 v138, v138
	v_rcp_f32_e32 v139, v139
	v_rcp_f32_e32 v140, v140
	v_rcp_f32_e32 v141, v141
	v_rcp_f32_e32 v142, v142
	v_rcp_f32_e32 v143, v143
	v_pk_mul_f32 v[136:137], v[128:129], v[136:137]
	v_pk_mul_f32 v[138:139], v[130:131], v[138:139]
	v_pk_mul_f32 v[140:141], v[132:133], v[140:141]
	v_pk_mul_f32 v[142:143], v[134:135], v[142:143]
	v_cvt_pk_bf16_f32 v144, v136, v137
	v_cvt_pk_bf16_f32 v145, v138, v139
	v_cvt_pk_bf16_f32 v146, v140, v141
	v_cvt_pk_bf16_f32 v147, v142, v143
	global_store_dwordx4 v182, v[144:147], s[12:13]
	v_pk_mul_f32 v[128:129], v[76:77], v[184:185] op_sel_hi:[1,0]
	v_pk_mul_f32 v[130:131], v[78:79], v[184:185] op_sel_hi:[1,0]
	v_pk_mul_f32 v[132:133], v[72:73], v[184:185] op_sel_hi:[1,0]
	v_pk_mul_f32 v[134:135], v[74:75], v[184:185] op_sel_hi:[1,0]
	v_pk_mul_f32 v[136:137], v[128:129], v[188:189] op_sel_hi:[1,0]
; __device__ __forceinline__ v4u pack8(const f32x4 a, const f32x4 b) { v4u w; w.x = cvt_pk_bf16(a[0], a[1]); w.y = cvt_pk_bf16(a[2], a[3]); w.z = cvt_pk_bf16(b[0], b[1]); w.w = cvt_pk_bf16(b[2], b[3]); return w; }
; __device__ __forceinline__ float silu_f(float x) { return x * __builtin_amdgcn_rcpf(1.f + __expf(-x)); }
;     __device__ __forceinline__ void operator()(const f32x4 (&acc)[2][2][4][2], const pg8::Unit& u, int wr, int wc, int fr, int fq) const {
;     ...
;         if (grp == 0) { WIN_LOOP( _Pragma("unroll") for (int i = 0; i < 4; ++i) { a[i] = silu_f(a[i]); b[i] = silu_f(b[i]); } *(v4u*)(QO + (size_t)row * DM + c) = pack8(a, b); ) }
;         else if (grp == 3) { WIN_LOOP( _Pragma("unroll") for (int i = 0; i < 4; ++i) { a[i] = silu_f(a[i]); b[i] = silu_f(b[i]); } *(v4u*)(GH + (size_t)row * 512 + c) = pack8(a, b); ) }
	v_pk_mul_f32 v[138:139], v[130:131], v[188:189] op_sel_hi:[1,0]
	v_pk_mul_f32 v[140:141], v[132:133], v[188:189] op_sel_hi:[1,0]
	v_pk_mul_f32 v[142:143], v[134:135], v[188:189] op_sel_hi:[1,0]
	v_exp_f32_e32 v136, v136
	v_exp_f32_e32 v137, v137
	v_exp_f32_e32 v138, v138
	v_exp_f32_e32 v139, v139
	v_exp_f32_e32 v140, v140
	v_exp_f32_e32 v141, v141
	v_exp_f32_e32 v142, v142
	v_exp_f32_e32 v143, v143
	v_pk_add_f32 v[136:137], v[136:137], 1.0 op_sel_hi:[1,0]
	v_pk_add_f32 v[138:139], v[138:139], 1.0 op_sel_hi:[1,0]
	v_pk_add_f32 v[140:141], v[140:141], 1.0 op_sel_hi:[1,0]
	v_pk_add_f32 v[142:143], v[142:143], 1.0 op_sel_hi:[1,0]
	v_rcp_f32_e32 v136, v136
	v_rcp_f32_e32 v137, v137
	v_rcp_f32_e32 v138, v138
	v_rcp_f32_e32 v139, v139
	v_rcp_f32_e32 v140, v140
	v_rcp_f32_e32 v141, v141
	v_rcp_f32_e32 v142, v142
	v_rcp_f32_e32 v143, v143
	v_pk_mul_f32 v[136:137], v[128:129], v[136:137]
	v_pk_mul_f32 v[138:139], v[130:131], v[138:139]
	v_pk_mul_f32 v[140:141], v[132:133], v[140:141]
	v_pk_mul_f32 v[142:143], v[134:135], v[142:143]
	v_cvt_pk_bf16_f32 v148, v136, v137
	v_cvt_pk_bf16_f32 v149, v138, v139
	v_cvt_pk_bf16_f32 v150, v140, v141
	v_cvt_pk_bf16_f32 v151, v142, v143
	global_store_dwordx4 v182, v[148:151], s[12:13] offset:256
	v_add_u32_e32 v181, 176, v166
	v_lshl_add_u32 v183, v181, 10, v192
	v_mov_b32_e32 v186, v245
	v_pk_mul_f32 v[128:129], v[4:5], v[186:187] op_sel_hi:[1,0]
	v_pk_mul_f32 v[130:131], v[6:7], v[186:187] op_sel_hi:[1,0]
	v_pk_mul_f32 v[132:133], v[0:1], v[186:187] op_sel_hi:[1,0]
	v_pk_mul_f32 v[134:135], v[2:3], v[186:187] op_sel_hi:[1,0]
	v_pk_mul_f32 v[136:137], v[128:129], v[188:189] op_sel_hi:[1,0]
	v_pk_mul_f32 v[138:139], v[130:131], v[188:189] op_sel_hi:[1,0]
	v_pk_mul_f32 v[140:141], v[132:133], v[188:189] op_sel_hi:[1,0]
	v_pk_mul_f32 v[142:143], v[134:135], v[188:189] op_sel_hi:[1,0]
	v_exp_f32_e32 v136, v136
	v_exp_f32_e32 v137, v137
	v_exp_f32_e32 v138, v138
	v_exp_f32_e32 v139, v139
	v_exp_f32_e32 v140, v140
	v_exp_f32_e32 v141, v141
	v_exp_f32_e32 v142, v142
	v_exp_f32_e32 v143, v143
	v_pk_add_f32 v[136:137], v[136:137], 1.0 op_sel_hi:[1,0]
	v_pk_add_f32 v[138:139], v[138:139], 1.0 op_sel_hi:[1,0]
	v_pk_add_f32 v[140:141], v[140:141], 1.0 op_sel_hi:[1,0]
	v_pk_add_f32 v[142:143], v[142:143], 1.0 op_sel_hi:[1,0]
	v_rcp_f32_e32 v136, v136
	v_rcp_f32_e32 v137, v137
	v_rcp_f32_e32 v138, v138
	v_rcp_f32_e32 v139, v139
	v_rcp_f32_e32 v140, v140
	v_rcp_f32_e32 v141, v141
	v_rcp_f32_e32 v142, v142
	v_rcp_f32_e32 v143, v143
	v_pk_mul_f32 v[136:137], v[128:129], v[136:137]
	v_pk_mul_f32 v[138:139], v[130:131], v[138:139]
	v_pk_mul_f32 v[140:141], v[132:133], v[140:141]
	v_pk_mul_f32 v[142:143], v[134:135], v[142:143]
	v_cvt_pk_bf16_f32 v144, v136, v137
	v_cvt_pk_bf16_f32 v145, v138, v139
	v_cvt_pk_bf16_f32 v146, v140, v141
	v_cvt_pk_bf16_f32 v147, v142, v143
	global_store_dwordx4 v183, v[144:147], s[12:13]
	v_pk_mul_f32 v[128:129], v[68:69], v[186:187] op_sel_hi:[1,0]
	v_pk_mul_f32 v[130:131], v[70:71], v[186:187] op_sel_hi:[1,0]
	v_pk_mul_f32 v[132:133], v[64:65], v[186:187] op_sel_hi:[1,0]
	v_pk_mul_f32 v[134:135], v[66:67], v[186:187] op_sel_hi:[1,0]
	v_pk_mul_f32 v[136:137], v[128:129], v[188:189] op_sel_hi:[1,0]
	v_pk_mul_f32 v[138:139], v[130:131], v[188:189] op_sel_hi:[1,0]
	v_pk_mul_f32 v[140:141], v[132:133], v[188:189] op_sel_hi:[1,0]
	v_pk_mul_f32 v[142:143], v[134:135], v[188:189] op_sel_hi:[1,0]
	v_exp_f32_e32 v136, v136
	v_exp_f32_e32 v137, v137
	v_exp_f32_e32 v138, v138
	v_exp_f32_e32 v139, v139
	v_exp_f32_e32 v140, v140
	v_exp_f32_e32 v141, v141
	v_exp_f32_e32 v142, v142
	v_exp_f32_e32 v143, v143
	v_pk_add_f32 v[136:137], v[136:137], 1.0 op_sel_hi:[1,0]
	v_pk_add_f32 v[138:139], v[138:139], 1.0 op_sel_hi:[1,0]
	v_pk_add_f32 v[140:141], v[140:141], 1.0 op_sel_hi:[1,0]
	v_pk_add_f32 v[142:143], v[142:143], 1.0 op_sel_hi:[1,0]
	v_rcp_f32_e32 v136, v136
	v_rcp_f32_e32 v137, v137
	v_rcp_f32_e32 v138, v138
	v_rcp_f32_e32 v139, v139
	v_rcp_f32_e32 v140, v140
	v_rcp_f32_e32 v141, v141
	v_rcp_f32_e32 v142, v142
	v_rcp_f32_e32 v143, v143
	v_pk_mul_f32 v[136:137], v[128:129], v[136:137]
	v_pk_mul_f32 v[138:139], v[130:131], v[138:139]
	v_pk_mul_f32 v[140:141], v[132:133], v[140:141]
	v_pk_mul_f32 v[142:143], v[134:135], v[142:143]
	v_cvt_pk_bf16_f32 v148, v136, v137
	v_cvt_pk_bf16_f32 v149, v138, v139
	v_cvt_pk_bf16_f32 v150, v140, v141
	v_cvt_pk_bf16_f32 v151, v142, v143
	global_store_dwordx4 v183, v[148:151], s[12:13] offset:256

; __device__ __forceinline__ v4u pack8(const f32x4 a, const f32x4 b) { v4u w; w.x = cvt_pk_bf16(a[0], a[1]); w.y = cvt_pk_bf16(a[2], a[3]); w.z = cvt_pk_bf16(b[0], b[1]); w.w = cvt_pk_bf16(b[2], b[3]); return w; }
; __device__ __forceinline__ float silu_f(float x) { return x * __builtin_amdgcn_rcpf(1.f + __expf(-x)); }
;     __device__ __forceinline__ void operator()(const f32x4 (&acc)[2][2][4][2], const pg8::Unit& u, int wr, int wc, int fr, int fq) const {
;     ...
;         if (grp == 0) { WIN_LOOP( _Pragma("unroll") for (int i = 0; i < 4; ++i) { a[i] = silu_f(a[i]); b[i] = silu_f(b[i]); } *(v4u*)(QO + (size_t)row * DM + c) = pack8(a, b); ) }
;         else if (grp == 3) { WIN_LOOP( _Pragma("unroll") for (int i = 0; i < 4; ++i) { a[i] = silu_f(a[i]); b[i] = silu_f(b[i]); } *(v4u*)(GH + (size_t)row * 512 + c) = pack8(a, b); ) }
.LBB0_417:
	s_and_b64 vcc, exec, s[8:9]
	s_cbranch_vccz .LBB0_419
	v_lshlrev_b32_e32 v192, 1, v176
	v_mov_b32_e32 v188, 0xbfb8aa3b
	v_lshl_add_u32 v182, v166, 11, v192
	v_mov_b32_e32 v184, v250
	v_pk_mul_f32 v[128:129], v[60:61], v[184:185] op_sel_hi:[1,0]
	v_pk_mul_f32 v[130:131], v[62:63], v[184:185] op_sel_hi:[1,0]
	v_pk_mul_f32 v[132:133], v[56:57], v[184:185] op_sel_hi:[1,0]
	v_pk_mul_f32 v[134:135], v[58:59], v[184:185] op_sel_hi:[1,0]
	v_pk_mul_f32 v[136:137], v[128:129], v[188:189] op_sel_hi:[1,0]
	v_pk_mul_f32 v[138:139], v[130:131], v[188:189] op_sel_hi:[1,0]
	v_pk_mul_f32 v[140:141], v[132:133], v[188:189] op_sel_hi:[1,0]
	v_pk_mul_f32 v[142:143], v[134:135], v[188:189] op_sel_hi:[1,0]
	v_exp_f32_e32 v136, v136
	v_exp_f32_e32 v137, v137
	v_exp_f32_e32 v138, v138
	v_exp_f32_e32 v139, v139
	v_exp_f32_e32 v140, v140
	v_exp_f32_e32 v141, v141
	v_exp_f32_e32 v142, v142
	v_exp_f32_e32 v143, v143
	v_pk_add_f32 v[136:137], v[136:137], 1.0 op_sel_hi:[1,0]
	v_pk_add_f32 v[138:139], v[138:139], 1.0 op_sel_hi:[1,0]
	v_pk_add_f32 v[140:141], v[140:141], 1.0 op_sel_hi:[1,0]
	v_pk_add_f32 v[142:143], v[142:143], 1.0 op_sel_hi:[1,0]
	v_rcp_f32_e32 v136, v136
	v_rcp_f32_e32 v137, v137
	v_rcp_f32_e32 v138, v138
	v_rcp_f32_e32 v139, v139
	v_rcp_f32_e32 v140, v140
	v_rcp_f32_e32 v141, v141
	v_rcp_f32_e32 v142, v142
	v_rcp_f32_e32 v143, v143
	v_pk_mul_f32 v[136:137], v[128:129], v[136:137]
	v_pk_mul_f32 v[138:139], v[130:131], v[138:139]
	v_pk_mul_f32 v[140:141], v[132:133], v[140:141]
	v_pk_mul_f32 v[142:143], v[134:135], v[142:143]
	v_cvt_pk_bf16_f32 v144, v136, v137
	v_cvt_pk_bf16_f32 v145, v138, v139
	v_cvt_pk_bf16_f32 v146, v140, v141
	v_cvt_pk_bf16_f32 v147, v142, v143
	global_store_dwordx4 v182, v[144:147], s[44:45]
	v_pk_mul_f32 v[128:129], v[124:125], v[184:185] op_sel_hi:[1,0]
	v_pk_mul_f32 v[130:131], v[126:127], v[184:185] op_sel_hi:[1,0]
	v_pk_mul_f32 v[132:133], v[120:121], v[184:185] op_sel_hi:[1,0]
	v_pk_mul_f32 v[134:135], v[122:123], v[184:185] op_sel_hi:[1,0]
	v_pk_mul_f32 v[136:137], v[128:129], v[188:189] op_sel_hi:[1,0]
	v_pk_mul_f32 v[138:139], v[130:131], v[188:189] op_sel_hi:[1,0]
	v_pk_mul_f32 v[140:141], v[132:133], v[188:189] op_sel_hi:[1,0]
	v_pk_mul_f32 v[142:143], v[134:135], v[188:189] op_sel_hi:[1,0]
	v_exp_f32_e32 v136, v136
	v_exp_f32_e32 v137, v137
	v_exp_f32_e32 v138, v138
	v_exp_f32_e32 v139, v139
	v_exp_f32_e32 v140, v140
	v_exp_f32_e32 v141, v141
	v_exp_f32_e32 v142, v142
	v_exp_f32_e32 v143, v143
	v_pk_add_f32 v[136:137], v[136:137], 1.0 op_sel_hi:[1,0]
	v_pk_add_f32 v[138:139], v[138:139], 1.0 op_sel_hi:[1,0]
	v_pk_add_f32 v[140:141], v[140:141], 1.0 op_sel_hi:[1,0]
	v_pk_add_f32 v[142:143], v[142:143], 1.0 op_sel_hi:[1,0]
	v_rcp_f32_e32 v136, v136
	v_rcp_f32_e32 v137, v137
	v_rcp_f32_e32 v138, v138
	v_rcp_f32_e32 v139, v139
	v_rcp_f32_e32 v140, v140
	v_rcp_f32_e32 v141, v141
	v_rcp_f32_e32 v142, v142
	v_rcp_f32_e32 v143, v143
	v_pk_mul_f32 v[136:137], v[128:129], v[136:137]
	v_pk_mul_f32 v[138:139], v[130:131], v[138:139]
	v_pk_mul_f32 v[140:141], v[132:133], v[140:141]
	v_pk_mul_f32 v[142:143], v[134:135], v[142:143]
	v_cvt_pk_bf16_f32 v148, v136, v137
	v_cvt_pk_bf16_f32 v149, v138, v139
	v_cvt_pk_bf16_f32 v150, v140, v141
	v_cvt_pk_bf16_f32 v151, v142, v143
	global_store_dwordx4 v182, v[148:151], s[44:45] offset:256
	v_add_u32_e32 v181, 16, v166
	v_lshl_add_u32 v183, v181, 11, v192
	v_mov_b32_e32 v186, v251
	v_pk_mul_f32 v[128:129], v[52:53], v[186:187] op_sel_hi:[1,0]
	v_pk_mul_f32 v[130:131], v[54:55], v[186:187] op_sel_hi:[1,0]
	v_pk_mul_f32 v[132:133], v[48:49], v[186:187] op_sel_hi:[1,0]
	v_pk_mul_f32 v[134:135], v[50:51], v[186:187] op_sel_hi:[1,0]
	v_pk_mul_f32 v[136:137], v[128:129], v[188:189] op_sel_hi:[1,0]
	v_pk_mul_f32 v[138:139], v[130:131], v[188:189] op_sel_hi:[1,0]
	v_pk_mul_f32 v[140:141], v[132:133], v[188:189] op_sel_hi:[1,0]
	v_pk_mul_f32 v[142:143], v[134:135], v[188:189] op_sel_hi:[1,0]
	v_exp_f32_e32 v136, v136
	v_exp_f32_e32 v137, v137
	v_exp_f32_e32 v138, v138
	v_exp_f32_e32 v139, v139
	v_exp_f32_e32 v140, v140
	v_exp_f32_e32 v141, v141
	v_exp_f32_e32 v142, v142
	v_exp_f32_e32 v143, v143
	v_pk_add_f32 v[136:137], v[136:137], 1.0 op_sel_hi:[1,0]
	v_pk_add_f32 v[138:139], v[138:139], 1.0 op_sel_hi:[1,0]
	v_pk_add_f32 v[140:141], v[140:141], 1.0 op_sel_hi:[1,0]
	v_pk_add_f32 v[142:143], v[142:143], 1.0 op_sel_hi:[1,0]
	v_rcp_f32_e32 v136, v136
	v_rcp_f32_e32 v137, v137
	v_rcp_f32_e32 v138, v138
	v_rcp_f32_e32 v139, v139
	v_rcp_f32_e32 v140, v140
	v_rcp_f32_e32 v141, v141
	v_rcp_f32_e32 v142, v142
	v_rcp_f32_e32 v143, v143
	v_pk_mul_f32 v[136:137], v[128:129], v[136:137]
	v_pk_mul_f32 v[138:139], v[130:131], v[138:139]
	v_pk_mul_f32 v[140:141], v[132:133], v[140:141]
	v_pk_mul_f32 v[142:143], v[134:135], v[142:143]
	v_cvt_pk_bf16_f32 v144, v136, v137
	v_cvt_pk_bf16_f32 v145, v138, v139
	v_cvt_pk_bf16_f32 v146, v140, v141
	v_cvt_pk_bf16_f32 v147, v142, v143
	global_store_dwordx4 v183, v[144:147], s[44:45]
	v_pk_mul_f32 v[128:129], v[116:117], v[186:187] op_sel_hi:[1,0]
	v_pk_mul_f32 v[130:131], v[118:119], v[186:187] op_sel_hi:[1,0]
	v_pk_mul_f32 v[132:133], v[112:113], v[186:187] op_sel_hi:[1,0]
	v_pk_mul_f32 v[134:135], v[114:115], v[186:187] op_sel_hi:[1,0]
	v_pk_mul_f32 v[136:137], v[128:129], v[188:189] op_sel_hi:[1,0]
	v_pk_mul_f32 v[138:139], v[130:131], v[188:189] op_sel_hi:[1,0]
	v_pk_mul_f32 v[140:141], v[132:133], v[188:189] op_sel_hi:[1,0]
	v_pk_mul_f32 v[142:143], v[134:135], v[188:189] op_sel_hi:[1,0]
	v_exp_f32_e32 v136, v136
	v_exp_f32_e32 v137, v137
	v_exp_f32_e32 v138, v138
	v_exp_f32_e32 v139, v139
	v_exp_f32_e32 v140, v140
	v_exp_f32_e32 v141, v141
; __device__ __forceinline__ v4u pack8(const f32x4 a, const f32x4 b) { v4u w; w.x = cvt_pk_bf16(a[0], a[1]); w.y = cvt_pk_bf16(a[2], a[3]); w.z = cvt_pk_bf16(b[0], b[1]); w.w = cvt_pk_bf16(b[2], b[3]); return w; }
; __device__ __forceinline__ float silu_f(float x) { return x * __builtin_amdgcn_rcpf(1.f + __expf(-x)); }
;     __device__ __forceinline__ void operator()(const f32x4 (&acc)[2][2][4][2], const pg8::Unit& u, int wr, int wc, int fr, int fq) const {
;     ...
;         if (grp == 0) { WIN_LOOP( _Pragma("unroll") for (int i = 0; i < 4; ++i) { a[i] = silu_f(a[i]); b[i] = silu_f(b[i]); } *(v4u*)(QO + (size_t)row * DM + c) = pack8(a, b); ) }
;         else if (grp == 3) { WIN_LOOP( _Pragma("unroll") for (int i = 0; i < 4; ++i) { a[i] = silu_f(a[i]); b[i] = silu_f(b[i]); } *(v4u*)(GH + (size_t)row * 512 + c) = pack8(a, b); ) }
	v_exp_f32_e32 v142, v142
	v_exp_f32_e32 v143, v143
	v_pk_add_f32 v[136:137], v[136:137], 1.0 op_sel_hi:[1,0]
	v_pk_add_f32 v[138:139], v[138:139], 1.0 op_sel_hi:[1,0]
	v_pk_add_f32 v[140:141], v[140:141], 1.0 op_sel_hi:[1,0]
	v_pk_add_f32 v[142:143], v[142:143], 1.0 op_sel_hi:[1,0]
	v_rcp_f32_e32 v136, v136
	v_rcp_f32_e32 v137, v137
	v_rcp_f32_e32 v138, v138
	v_rcp_f32_e32 v139, v139
	v_rcp_f32_e32 v140, v140
	v_rcp_f32_e32 v141, v141
	v_rcp_f32_e32 v142, v142
	v_rcp_f32_e32 v143, v143
	v_pk_mul_f32 v[136:137], v[128:129], v[136:137]
	v_pk_mul_f32 v[138:139], v[130:131], v[138:139]
	v_pk_mul_f32 v[140:141], v[132:133], v[140:141]
	v_pk_mul_f32 v[142:143], v[134:135], v[142:143]
	v_cvt_pk_bf16_f32 v148, v136, v137
	v_cvt_pk_bf16_f32 v149, v138, v139
	v_cvt_pk_bf16_f32 v150, v140, v141
	v_cvt_pk_bf16_f32 v151, v142, v143
	global_store_dwordx4 v183, v[148:151], s[44:45] offset:256
	v_add_u32_e32 v180, 32, v166
	v_lshl_add_u32 v182, v180, 11, v192
	v_mov_b32_e32 v184, v252
	v_pk_mul_f32 v[128:129], v[44:45], v[184:185] op_sel_hi:[1,0]
	v_pk_mul_f32 v[130:131], v[46:47], v[184:185] op_sel_hi:[1,0]
	v_pk_mul_f32 v[132:133], v[40:41], v[184:185] op_sel_hi:[1,0]
	v_pk_mul_f32 v[134:135], v[42:43], v[184:185] op_sel_hi:[1,0]
	v_pk_mul_f32 v[136:137], v[128:129], v[188:189] op_sel_hi:[1,0]
	v_pk_mul_f32 v[138:139], v[130:131], v[188:189] op_sel_hi:[1,0]
	v_pk_mul_f32 v[140:141], v[132:133], v[188:189] op_sel_hi:[1,0]
	v_pk_mul_f32 v[142:143], v[134:135], v[188:189] op_sel_hi:[1,0]
	v_exp_f32_e32 v136, v136
	v_exp_f32_e32 v137, v137
	v_exp_f32_e32 v138, v138
	v_exp_f32_e32 v139, v139
	v_exp_f32_e32 v140, v140
	v_exp_f32_e32 v141, v141
	v_exp_f32_e32 v142, v142
	v_exp_f32_e32 v143, v143
	v_pk_add_f32 v[136:137], v[136:137], 1.0 op_sel_hi:[1,0]
	v_pk_add_f32 v[138:139], v[138:139], 1.0 op_sel_hi:[1,0]
	v_pk_add_f32 v[140:141], v[140:141], 1.0 op_sel_hi:[1,0]
	v_pk_add_f32 v[142:143], v[142:143], 1.0 op_sel_hi:[1,0]
	v_rcp_f32_e32 v136, v136
	v_rcp_f32_e32 v137, v137
	v_rcp_f32_e32 v138, v138
	v_rcp_f32_e32 v139, v139
	v_rcp_f32_e32 v140, v140
	v_rcp_f32_e32 v141, v141
	v_rcp_f32_e32 v142, v142
	v_rcp_f32_e32 v143, v143
	v_pk_mul_f32 v[136:137], v[128:129], v[136:137]
	v_pk_mul_f32 v[138:139], v[130:131], v[138:139]
	v_pk_mul_f32 v[140:141], v[132:133], v[140:141]
	v_pk_mul_f32 v[142:143], v[134:135], v[142:143]
	v_cvt_pk_bf16_f32 v144, v136, v137
	v_cvt_pk_bf16_f32 v145, v138, v139
	v_cvt_pk_bf16_f32 v146, v140, v141
	v_cvt_pk_bf16_f32 v147, v142, v143
	global_store_dwordx4 v182, v[144:147], s[44:45]
	v_pk_mul_f32 v[128:129], v[108:109], v[184:185] op_sel_hi:[1,0]
	v_pk_mul_f32 v[130:131], v[110:111], v[184:185] op_sel_hi:[1,0]
	v_pk_mul_f32 v[132:133], v[104:105], v[184:185] op_sel_hi:[1,0]
	v_pk_mul_f32 v[134:135], v[106:107], v[184:185] op_sel_hi:[1,0]
	v_pk_mul_f32 v[136:137], v[128:129], v[188:189] op_sel_hi:[1,0]
	v_pk_mul_f32 v[138:139], v[130:131], v[188:189] op_sel_hi:[1,0]
	v_pk_mul_f32 v[140:141], v[132:133], v[188:189] op_sel_hi:[1,0]
	v_pk_mul_f32 v[142:143], v[134:135], v[188:189] op_sel_hi:[1,0]
	v_exp_f32_e32 v136, v136
	v_exp_f32_e32 v137, v137
	v_exp_f32_e32 v138, v138
	v_exp_f32_e32 v139, v139
	v_exp_f32_e32 v140, v140
	v_exp_f32_e32 v141, v141
	v_exp_f32_e32 v142, v142
	v_exp_f32_e32 v143, v143
	v_pk_add_f32 v[136:137], v[136:137], 1.0 op_sel_hi:[1,0]
	v_pk_add_f32 v[138:139], v[138:139], 1.0 op_sel_hi:[1,0]
	v_pk_add_f32 v[140:141], v[140:141], 1.0 op_sel_hi:[1,0]
	v_pk_add_f32 v[142:143], v[142:143], 1.0 op_sel_hi:[1,0]
	v_rcp_f32_e32 v136, v136
	v_rcp_f32_e32 v137, v137
	v_rcp_f32_e32 v138, v138
	v_rcp_f32_e32 v139, v139
	v_rcp_f32_e32 v140, v140
	v_rcp_f32_e32 v141, v141
	v_rcp_f32_e32 v142, v142
	v_rcp_f32_e32 v143, v143
	v_pk_mul_f32 v[136:137], v[128:129], v[136:137]
	v_pk_mul_f32 v[138:139], v[130:131], v[138:139]
	v_pk_mul_f32 v[140:141], v[132:133], v[140:141]
	v_pk_mul_f32 v[142:143], v[134:135], v[142:143]
	v_cvt_pk_bf16_f32 v148, v136, v137
	v_cvt_pk_bf16_f32 v149, v138, v139
	v_cvt_pk_bf16_f32 v150, v140, v141
	v_cvt_pk_bf16_f32 v151, v142, v143
	global_store_dwordx4 v182, v[148:151], s[44:45] offset:256
	v_add_u32_e32 v181, 48, v166
	v_lshl_add_u32 v183, v181, 11, v192
	v_mov_b32_e32 v186, v253
	v_pk_mul_f32 v[128:129], v[36:37], v[186:187] op_sel_hi:[1,0]
	v_pk_mul_f32 v[130:131], v[38:39], v[186:187] op_sel_hi:[1,0]
	v_pk_mul_f32 v[132:133], v[32:33], v[186:187] op_sel_hi:[1,0]
	v_pk_mul_f32 v[134:135], v[34:35], v[186:187] op_sel_hi:[1,0]
	v_pk_mul_f32 v[136:137], v[128:129], v[188:189] op_sel_hi:[1,0]
	v_pk_mul_f32 v[138:139], v[130:131], v[188:189] op_sel_hi:[1,0]
	v_pk_mul_f32 v[140:141], v[132:133], v[188:189] op_sel_hi:[1,0]
	v_pk_mul_f32 v[142:143], v[134:135], v[188:189] op_sel_hi:[1,0]
	v_exp_f32_e32 v136, v136
	v_exp_f32_e32 v137, v137
	v_exp_f32_e32 v138, v138
	v_exp_f32_e32 v139, v139
	v_exp_f32_e32 v140, v140
	v_exp_f32_e32 v141, v141
	v_exp_f32_e32 v142, v142
	v_exp_f32_e32 v143, v143
	v_pk_add_f32 v[136:137], v[136:137], 1.0 op_sel_hi:[1,0]
	v_pk_add_f32 v[138:139], v[138:139], 1.0 op_sel_hi:[1,0]
	v_pk_add_f32 v[140:141], v[140:141], 1.0 op_sel_hi:[1,0]
	v_pk_add_f32 v[142:143], v[142:143], 1.0 op_sel_hi:[1,0]
	v_rcp_f32_e32 v136, v136
	v_rcp_f32_e32 v137, v137
	v_rcp_f32_e32 v138, v138
	v_rcp_f32_e32 v139, v139
	v_rcp_f32_e32 v140, v140
	v_rcp_f32_e32 v141, v141
	v_rcp_f32_e32 v142, v142
	v_rcp_f32_e32 v143, v143
	v_pk_mul_f32 v[136:137], v[128:129], v[136:137]
	v_pk_mul_f32 v[138:139], v[130:131], v[138:139]
	v_pk_mul_f32 v[140:141], v[132:133], v[140:141]
	v_pk_mul_f32 v[142:143], v[134:135], v[142:143]
	v_cvt_pk_bf16_f32 v144, v136, v137
	v_cvt_pk_bf16_f32 v145, v138, v139
; __device__ __forceinline__ v4u pack8(const f32x4 a, const f32x4 b) { v4u w; w.x = cvt_pk_bf16(a[0], a[1]); w.y = cvt_pk_bf16(a[2], a[3]); w.z = cvt_pk_bf16(b[0], b[1]); w.w = cvt_pk_bf16(b[2], b[3]); return w; }
; __device__ __forceinline__ float silu_f(float x) { return x * __builtin_amdgcn_rcpf(1.f + __expf(-x)); }
;     __device__ __forceinline__ void operator()(const f32x4 (&acc)[2][2][4][2], const pg8::Unit& u, int wr, int wc, int fr, int fq) const {
;     ...
;         if (grp == 0) { WIN_LOOP( _Pragma("unroll") for (int i = 0; i < 4; ++i) { a[i] = silu_f(a[i]); b[i] = silu_f(b[i]); } *(v4u*)(QO + (size_t)row * DM + c) = pack8(a, b); ) }
;         else if (grp == 3) { WIN_LOOP( _Pragma("unroll") for (int i = 0; i < 4; ++i) { a[i] = silu_f(a[i]); b[i] = silu_f(b[i]); } *(v4u*)(GH + (size_t)row * 512 + c) = pack8(a, b); ) }
	v_cvt_pk_bf16_f32 v146, v140, v141
	v_cvt_pk_bf16_f32 v147, v142, v143
	global_store_dwordx4 v183, v[144:147], s[44:45]
	v_pk_mul_f32 v[128:129], v[100:101], v[186:187] op_sel_hi:[1,0]
	v_pk_mul_f32 v[130:131], v[102:103], v[186:187] op_sel_hi:[1,0]
	v_pk_mul_f32 v[132:133], v[96:97], v[186:187] op_sel_hi:[1,0]
	v_pk_mul_f32 v[134:135], v[98:99], v[186:187] op_sel_hi:[1,0]
	v_pk_mul_f32 v[136:137], v[128:129], v[188:189] op_sel_hi:[1,0]
	v_pk_mul_f32 v[138:139], v[130:131], v[188:189] op_sel_hi:[1,0]
	v_pk_mul_f32 v[140:141], v[132:133], v[188:189] op_sel_hi:[1,0]
	v_pk_mul_f32 v[142:143], v[134:135], v[188:189] op_sel_hi:[1,0]
	v_exp_f32_e32 v136, v136
	v_exp_f32_e32 v137, v137
	v_exp_f32_e32 v138, v138
	v_exp_f32_e32 v139, v139
	v_exp_f32_e32 v140, v140
	v_exp_f32_e32 v141, v141
	v_exp_f32_e32 v142, v142
	v_exp_f32_e32 v143, v143
	v_pk_add_f32 v[136:137], v[136:137], 1.0 op_sel_hi:[1,0]
	v_pk_add_f32 v[138:139], v[138:139], 1.0 op_sel_hi:[1,0]
	v_pk_add_f32 v[140:141], v[140:141], 1.0 op_sel_hi:[1,0]
	v_pk_add_f32 v[142:143], v[142:143], 1.0 op_sel_hi:[1,0]
	v_rcp_f32_e32 v136, v136
	v_rcp_f32_e32 v137, v137
	v_rcp_f32_e32 v138, v138
	v_rcp_f32_e32 v139, v139
	v_rcp_f32_e32 v140, v140
	v_rcp_f32_e32 v141, v141
	v_rcp_f32_e32 v142, v142
	v_rcp_f32_e32 v143, v143
	v_pk_mul_f32 v[136:137], v[128:129], v[136:137]
	v_pk_mul_f32 v[138:139], v[130:131], v[138:139]
	v_pk_mul_f32 v[140:141], v[132:133], v[140:141]
	v_pk_mul_f32 v[142:143], v[134:135], v[142:143]
	v_cvt_pk_bf16_f32 v148, v136, v137
	v_cvt_pk_bf16_f32 v149, v138, v139
	v_cvt_pk_bf16_f32 v150, v140, v141
	v_cvt_pk_bf16_f32 v151, v142, v143
	global_store_dwordx4 v183, v[148:151], s[44:45] offset:256
	v_add_u32_e32 v180, 128, v166
	v_lshl_add_u32 v182, v180, 11, v192
	v_mov_b32_e32 v184, v254
	v_pk_mul_f32 v[128:129], v[28:29], v[184:185] op_sel_hi:[1,0]
	v_pk_mul_f32 v[130:131], v[30:31], v[184:185] op_sel_hi:[1,0]
	v_pk_mul_f32 v[132:133], v[24:25], v[184:185] op_sel_hi:[1,0]
	v_pk_mul_f32 v[134:135], v[26:27], v[184:185] op_sel_hi:[1,0]
	v_pk_mul_f32 v[136:137], v[128:129], v[188:189] op_sel_hi:[1,0]
	v_pk_mul_f32 v[138:139], v[130:131], v[188:189] op_sel_hi:[1,0]
	v_pk_mul_f32 v[140:141], v[132:133], v[188:189] op_sel_hi:[1,0]
	v_pk_mul_f32 v[142:143], v[134:135], v[188:189] op_sel_hi:[1,0]
	v_exp_f32_e32 v136, v136
	v_exp_f32_e32 v137, v137
	v_exp_f32_e32 v138, v138
	v_exp_f32_e32 v139, v139
	v_exp_f32_e32 v140, v140
	v_exp_f32_e32 v141, v141
	v_exp_f32_e32 v142, v142
	v_exp_f32_e32 v143, v143
	v_pk_add_f32 v[136:137], v[136:137], 1.0 op_sel_hi:[1,0]
	v_pk_add_f32 v[138:139], v[138:139], 1.0 op_sel_hi:[1,0]
	v_pk_add_f32 v[140:141], v[140:141], 1.0 op_sel_hi:[1,0]
	v_pk_add_f32 v[142:143], v[142:143], 1.0 op_sel_hi:[1,0]
	v_rcp_f32_e32 v136, v136
	v_rcp_f32_e32 v137, v137
	v_rcp_f32_e32 v138, v138
	v_rcp_f32_e32 v139, v139
	v_rcp_f32_e32 v140, v140
	v_rcp_f32_e32 v141, v141
	v_rcp_f32_e32 v142, v142
	v_rcp_f32_e32 v143, v143
	v_pk_mul_f32 v[136:137], v[128:129], v[136:137]
	v_pk_mul_f32 v[138:139], v[130:131], v[138:139]
	v_pk_mul_f32 v[140:141], v[132:133], v[140:141]
	v_pk_mul_f32 v[142:143], v[134:135], v[142:143]
	v_cvt_pk_bf16_f32 v144, v136, v137
	v_cvt_pk_bf16_f32 v145, v138, v139
	v_cvt_pk_bf16_f32 v146, v140, v141
	v_cvt_pk_bf16_f32 v147, v142, v143
	global_store_dwordx4 v182, v[144:147], s[44:45]
	v_pk_mul_f32 v[128:129], v[92:93], v[184:185] op_sel_hi:[1,0]
	v_pk_mul_f32 v[130:131], v[94:95], v[184:185] op_sel_hi:[1,0]
	v_pk_mul_f32 v[132:133], v[88:89], v[184:185] op_sel_hi:[1,0]
	v_pk_mul_f32 v[134:135], v[90:91], v[184:185] op_sel_hi:[1,0]
	v_pk_mul_f32 v[136:137], v[128:129], v[188:189] op_sel_hi:[1,0]
	v_pk_mul_f32 v[138:139], v[130:131], v[188:189] op_sel_hi:[1,0]
	v_pk_mul_f32 v[140:141], v[132:133], v[188:189] op_sel_hi:[1,0]
	v_pk_mul_f32 v[142:143], v[134:135], v[188:189] op_sel_hi:[1,0]
	v_exp_f32_e32 v136, v136
	v_exp_f32_e32 v137, v137
	v_exp_f32_e32 v138, v138
	v_exp_f32_e32 v139, v139
	v_exp_f32_e32 v140, v140
	v_exp_f32_e32 v141, v141
	v_exp_f32_e32 v142, v142
	v_exp_f32_e32 v143, v143
	v_pk_add_f32 v[136:137], v[136:137], 1.0 op_sel_hi:[1,0]
	v_pk_add_f32 v[138:139], v[138:139], 1.0 op_sel_hi:[1,0]
	v_pk_add_f32 v[140:141], v[140:141], 1.0 op_sel_hi:[1,0]
	v_pk_add_f32 v[142:143], v[142:143], 1.0 op_sel_hi:[1,0]
	v_rcp_f32_e32 v136, v136
	v_rcp_f32_e32 v137, v137
	v_rcp_f32_e32 v138, v138
	v_rcp_f32_e32 v139, v139
	v_rcp_f32_e32 v140, v140
	v_rcp_f32_e32 v141, v141
	v_rcp_f32_e32 v142, v142
	v_rcp_f32_e32 v143, v143
	v_pk_mul_f32 v[136:137], v[128:129], v[136:137]
	v_pk_mul_f32 v[138:139], v[130:131], v[138:139]
	v_pk_mul_f32 v[140:141], v[132:133], v[140:141]
	v_pk_mul_f32 v[142:143], v[134:135], v[142:143]
	v_cvt_pk_bf16_f32 v148, v136, v137
	v_cvt_pk_bf16_f32 v149, v138, v139
	v_cvt_pk_bf16_f32 v150, v140, v141
	v_cvt_pk_bf16_f32 v151, v142, v143
	global_store_dwordx4 v182, v[148:151], s[44:45] offset:256
	v_add_u32_e32 v181, 144, v166
	v_lshl_add_u32 v183, v181, 11, v192
	v_mov_b32_e32 v186, v240
	v_pk_mul_f32 v[128:129], v[20:21], v[186:187] op_sel_hi:[1,0]
	v_pk_mul_f32 v[130:131], v[22:23], v[186:187] op_sel_hi:[1,0]
	v_pk_mul_f32 v[132:133], v[16:17], v[186:187] op_sel_hi:[1,0]
	v_pk_mul_f32 v[134:135], v[18:19], v[186:187] op_sel_hi:[1,0]
	v_pk_mul_f32 v[136:137], v[128:129], v[188:189] op_sel_hi:[1,0]
	v_pk_mul_f32 v[138:139], v[130:131], v[188:189] op_sel_hi:[1,0]
	v_pk_mul_f32 v[140:141], v[132:133], v[188:189] op_sel_hi:[1,0]
	v_pk_mul_f32 v[142:143], v[134:135], v[188:189] op_sel_hi:[1,0]
	v_exp_f32_e32 v136, v136
	v_exp_f32_e32 v137, v137
	v_exp_f32_e32 v138, v138
	v_exp_f32_e32 v139, v139
	v_exp_f32_e32 v140, v140
	v_exp_f32_e32 v141, v141
; __device__ __forceinline__ v4u pack8(const f32x4 a, const f32x4 b) { v4u w; w.x = cvt_pk_bf16(a[0], a[1]); w.y = cvt_pk_bf16(a[2], a[3]); w.z = cvt_pk_bf16(b[0], b[1]); w.w = cvt_pk_bf16(b[2], b[3]); return w; }
; __device__ __forceinline__ float silu_f(float x) { return x * __builtin_amdgcn_rcpf(1.f + __expf(-x)); }
;     __device__ __forceinline__ void operator()(const f32x4 (&acc)[2][2][4][2], const pg8::Unit& u, int wr, int wc, int fr, int fq) const {
;     ...
;         if (grp == 0) { WIN_LOOP( _Pragma("unroll") for (int i = 0; i < 4; ++i) { a[i] = silu_f(a[i]); b[i] = silu_f(b[i]); } *(v4u*)(QO + (size_t)row * DM + c) = pack8(a, b); ) }
;         else if (grp == 3) { WIN_LOOP( _Pragma("unroll") for (int i = 0; i < 4; ++i) { a[i] = silu_f(a[i]); b[i] = silu_f(b[i]); } *(v4u*)(GH + (size_t)row * 512 + c) = pack8(a, b); ) }
	v_exp_f32_e32 v142, v142
	v_exp_f32_e32 v143, v143
	v_pk_add_f32 v[136:137], v[136:137], 1.0 op_sel_hi:[1,0]
	v_pk_add_f32 v[138:139], v[138:139], 1.0 op_sel_hi:[1,0]
	v_pk_add_f32 v[140:141], v[140:141], 1.0 op_sel_hi:[1,0]
	v_pk_add_f32 v[142:143], v[142:143], 1.0 op_sel_hi:[1,0]
	v_rcp_f32_e32 v136, v136
	v_rcp_f32_e32 v137, v137
	v_rcp_f32_e32 v138, v138
	v_rcp_f32_e32 v139, v139
	v_rcp_f32_e32 v140, v140
	v_rcp_f32_e32 v141, v141
	v_rcp_f32_e32 v142, v142
	v_rcp_f32_e32 v143, v143
	v_pk_mul_f32 v[136:137], v[128:129], v[136:137]
	v_pk_mul_f32 v[138:139], v[130:131], v[138:139]
	v_pk_mul_f32 v[140:141], v[132:133], v[140:141]
	v_pk_mul_f32 v[142:143], v[134:135], v[142:143]
	v_cvt_pk_bf16_f32 v144, v136, v137
	v_cvt_pk_bf16_f32 v145, v138, v139
	v_cvt_pk_bf16_f32 v146, v140, v141
	v_cvt_pk_bf16_f32 v147, v142, v143
	global_store_dwordx4 v183, v[144:147], s[44:45]
	v_pk_mul_f32 v[128:129], v[84:85], v[186:187] op_sel_hi:[1,0]
	v_pk_mul_f32 v[130:131], v[86:87], v[186:187] op_sel_hi:[1,0]
	v_pk_mul_f32 v[132:133], v[80:81], v[186:187] op_sel_hi:[1,0]
	v_pk_mul_f32 v[134:135], v[82:83], v[186:187] op_sel_hi:[1,0]
	v_pk_mul_f32 v[136:137], v[128:129], v[188:189] op_sel_hi:[1,0]
	v_pk_mul_f32 v[138:139], v[130:131], v[188:189] op_sel_hi:[1,0]
	v_pk_mul_f32 v[140:141], v[132:133], v[188:189] op_sel_hi:[1,0]
	v_pk_mul_f32 v[142:143], v[134:135], v[188:189] op_sel_hi:[1,0]
	v_exp_f32_e32 v136, v136
	v_exp_f32_e32 v137, v137
	v_exp_f32_e32 v138, v138
	v_exp_f32_e32 v139, v139
	v_exp_f32_e32 v140, v140
	v_exp_f32_e32 v141, v141
	v_exp_f32_e32 v142, v142
	v_exp_f32_e32 v143, v143
	v_pk_add_f32 v[136:137], v[136:137], 1.0 op_sel_hi:[1,0]
	v_pk_add_f32 v[138:139], v[138:139], 1.0 op_sel_hi:[1,0]
	v_pk_add_f32 v[140:141], v[140:141], 1.0 op_sel_hi:[1,0]
	v_pk_add_f32 v[142:143], v[142:143], 1.0 op_sel_hi:[1,0]
	v_rcp_f32_e32 v136, v136
	v_rcp_f32_e32 v137, v137
	v_rcp_f32_e32 v138, v138
	v_rcp_f32_e32 v139, v139
	v_rcp_f32_e32 v140, v140
	v_rcp_f32_e32 v141, v141
	v_rcp_f32_e32 v142, v142
	v_rcp_f32_e32 v143, v143
	v_pk_mul_f32 v[136:137], v[128:129], v[136:137]
	v_pk_mul_f32 v[138:139], v[130:131], v[138:139]
	v_pk_mul_f32 v[140:141], v[132:133], v[140:141]
	v_pk_mul_f32 v[142:143], v[134:135], v[142:143]
	v_cvt_pk_bf16_f32 v148, v136, v137
	v_cvt_pk_bf16_f32 v149, v138, v139
	v_cvt_pk_bf16_f32 v150, v140, v141
	v_cvt_pk_bf16_f32 v151, v142, v143
	global_store_dwordx4 v183, v[148:151], s[44:45] offset:256
	v_add_u32_e32 v180, 160, v166
	v_lshl_add_u32 v182, v180, 11, v192
	v_mov_b32_e32 v184, v241
	v_pk_mul_f32 v[128:129], v[12:13], v[184:185] op_sel_hi:[1,0]
	v_pk_mul_f32 v[130:131], v[14:15], v[184:185] op_sel_hi:[1,0]
	v_pk_mul_f32 v[132:133], v[8:9], v[184:185] op_sel_hi:[1,0]
	v_pk_mul_f32 v[134:135], v[10:11], v[184:185] op_sel_hi:[1,0]
	v_pk_mul_f32 v[136:137], v[128:129], v[188:189] op_sel_hi:[1,0]
	v_pk_mul_f32 v[138:139], v[130:131], v[188:189] op_sel_hi:[1,0]
	v_pk_mul_f32 v[140:141], v[132:133], v[188:189] op_sel_hi:[1,0]
	v_pk_mul_f32 v[142:143], v[134:135], v[188:189] op_sel_hi:[1,0]
	v_exp_f32_e32 v136, v136
	v_exp_f32_e32 v137, v137
	v_exp_f32_e32 v138, v138
	v_exp_f32_e32 v139, v139
	v_exp_f32_e32 v140, v140
	v_exp_f32_e32 v141, v141
	v_exp_f32_e32 v142, v142
	v_exp_f32_e32 v143, v143
	v_pk_add_f32 v[136:137], v[136:137], 1.0 op_sel_hi:[1,0]
	v_pk_add_f32 v[138:139], v[138:139], 1.0 op_sel_hi:[1,0]
	v_pk_add_f32 v[140:141], v[140:141], 1.0 op_sel_hi:[1,0]
	v_pk_add_f32 v[142:143], v[142:143], 1.0 op_sel_hi:[1,0]
	v_rcp_f32_e32 v136, v136
	v_rcp_f32_e32 v137, v137
	v_rcp_f32_e32 v138, v138
	v_rcp_f32_e32 v139, v139
	v_rcp_f32_e32 v140, v140
	v_rcp_f32_e32 v141, v141
	v_rcp_f32_e32 v142, v142
	v_rcp_f32_e32 v143, v143
	v_pk_mul_f32 v[136:137], v[128:129], v[136:137]
	v_pk_mul_f32 v[138:139], v[130:131], v[138:139]
	v_pk_mul_f32 v[140:141], v[132:133], v[140:141]
	v_pk_mul_f32 v[142:143], v[134:135], v[142:143]
	v_cvt_pk_bf16_f32 v144, v136, v137
	v_cvt_pk_bf16_f32 v145, v138, v139
	v_cvt_pk_bf16_f32 v146, v140, v141
	v_cvt_pk_bf16_f32 v147, v142, v143
	global_store_dwordx4 v182, v[144:147], s[44:45]
	v_pk_mul_f32 v[128:129], v[76:77], v[184:185] op_sel_hi:[1,0]
	v_pk_mul_f32 v[130:131], v[78:79], v[184:185] op_sel_hi:[1,0]
	v_pk_mul_f32 v[132:133], v[72:73], v[184:185] op_sel_hi:[1,0]
	v_pk_mul_f32 v[134:135], v[74:75], v[184:185] op_sel_hi:[1,0]
	v_pk_mul_f32 v[136:137], v[128:129], v[188:189] op_sel_hi:[1,0]
; __device__ __forceinline__ v4u pack8(const f32x4 a, const f32x4 b) { v4u w; w.x = cvt_pk_bf16(a[0], a[1]); w.y = cvt_pk_bf16(a[2], a[3]); w.z = cvt_pk_bf16(b[0], b[1]); w.w = cvt_pk_bf16(b[2], b[3]); return w; }
; __device__ __forceinline__ float silu_f(float x) { return x * __builtin_amdgcn_rcpf(1.f + __expf(-x)); }
;     __device__ __forceinline__ void operator()(const f32x4 (&acc)[2][2][4][2], const pg8::Unit& u, int wr, int wc, int fr, int fq) const {
;     ...
;         if (grp == 0) { WIN_LOOP( _Pragma("unroll") for (int i = 0; i < 4; ++i) { a[i] = silu_f(a[i]); b[i] = silu_f(b[i]); } *(v4u*)(QO + (size_t)row * DM + c) = pack8(a, b); ) }
;         else if (grp == 3) { WIN_LOOP( _Pragma("unroll") for (int i = 0; i < 4; ++i) { a[i] = silu_f(a[i]); b[i] = silu_f(b[i]); } *(v4u*)(GH + (size_t)row * 512 + c) = pack8(a, b); ) }
	v_pk_mul_f32 v[138:139], v[130:131], v[188:189] op_sel_hi:[1,0]
	v_pk_mul_f32 v[140:141], v[132:133], v[188:189] op_sel_hi:[1,0]
	v_pk_mul_f32 v[142:143], v[134:135], v[188:189] op_sel_hi:[1,0]
	v_exp_f32_e32 v136, v136
	v_exp_f32_e32 v137, v137
	v_exp_f32_e32 v138, v138
	v_exp_f32_e32 v139, v139
	v_exp_f32_e32 v140, v140
	v_exp_f32_e32 v141, v141
	v_exp_f32_e32 v142, v142
	v_exp_f32_e32 v143, v143
	v_pk_add_f32 v[136:137], v[136:137], 1.0 op_sel_hi:[1,0]
	v_pk_add_f32 v[138:139], v[138:139], 1.0 op_sel_hi:[1,0]
	v_pk_add_f32 v[140:141], v[140:141], 1.0 op_sel_hi:[1,0]
	v_pk_add_f32 v[142:143], v[142:143], 1.0 op_sel_hi:[1,0]
	v_rcp_f32_e32 v136, v136
	v_rcp_f32_e32 v137, v137
	v_rcp_f32_e32 v138, v138
	v_rcp_f32_e32 v139, v139
	v_rcp_f32_e32 v140, v140
	v_rcp_f32_e32 v141, v141
	v_rcp_f32_e32 v142, v142
	v_rcp_f32_e32 v143, v143
	v_pk_mul_f32 v[136:137], v[128:129], v[136:137]
	v_pk_mul_f32 v[138:139], v[130:131], v[138:139]
	v_pk_mul_f32 v[140:141], v[132:133], v[140:141]
	v_pk_mul_f32 v[142:143], v[134:135], v[142:143]
	v_cvt_pk_bf16_f32 v148, v136, v137
	v_cvt_pk_bf16_f32 v149, v138, v139
	v_cvt_pk_bf16_f32 v150, v140, v141
	v_cvt_pk_bf16_f32 v151, v142, v143
	global_store_dwordx4 v182, v[148:151], s[44:45] offset:256
	v_add_u32_e32 v181, 176, v166
	v_lshl_add_u32 v183, v181, 11, v192
	v_mov_b32_e32 v186, v245
	v_pk_mul_f32 v[128:129], v[4:5], v[186:187] op_sel_hi:[1,0]
	v_pk_mul_f32 v[130:131], v[6:7], v[186:187] op_sel_hi:[1,0]
	v_pk_mul_f32 v[132:133], v[0:1], v[186:187] op_sel_hi:[1,0]
	v_pk_mul_f32 v[134:135], v[2:3], v[186:187] op_sel_hi:[1,0]
	v_pk_mul_f32 v[136:137], v[128:129], v[188:189] op_sel_hi:[1,0]
	v_pk_mul_f32 v[138:139], v[130:131], v[188:189] op_sel_hi:[1,0]
	v_pk_mul_f32 v[140:141], v[132:133], v[188:189] op_sel_hi:[1,0]
	v_pk_mul_f32 v[142:143], v[134:135], v[188:189] op_sel_hi:[1,0]
	v_exp_f32_e32 v136, v136
	v_exp_f32_e32 v137, v137
	v_exp_f32_e32 v138, v138
	v_exp_f32_e32 v139, v139
	v_exp_f32_e32 v140, v140
	v_exp_f32_e32 v141, v141
	v_exp_f32_e32 v142, v142
	v_exp_f32_e32 v143, v143
	v_pk_add_f32 v[136:137], v[136:137], 1.0 op_sel_hi:[1,0]
	v_pk_add_f32 v[138:139], v[138:139], 1.0 op_sel_hi:[1,0]
	v_pk_add_f32 v[140:141], v[140:141], 1.0 op_sel_hi:[1,0]
	v_pk_add_f32 v[142:143], v[142:143], 1.0 op_sel_hi:[1,0]
	v_rcp_f32_e32 v136, v136
	v_rcp_f32_e32 v137, v137
	v_rcp_f32_e32 v138, v138
	v_rcp_f32_e32 v139, v139
	v_rcp_f32_e32 v140, v140
	v_rcp_f32_e32 v141, v141
	v_rcp_f32_e32 v142, v142
	v_rcp_f32_e32 v143, v143
	v_pk_mul_f32 v[136:137], v[128:129], v[136:137]
	v_pk_mul_f32 v[138:139], v[130:131], v[138:139]
	v_pk_mul_f32 v[140:141], v[132:133], v[140:141]
	v_pk_mul_f32 v[142:143], v[134:135], v[142:143]
	v_cvt_pk_bf16_f32 v144, v136, v137
	v_cvt_pk_bf16_f32 v145, v138, v139
	v_cvt_pk_bf16_f32 v146, v140, v141
	v_cvt_pk_bf16_f32 v147, v142, v143
	global_store_dwordx4 v183, v[144:147], s[44:45]
	v_pk_mul_f32 v[128:129], v[68:69], v[186:187] op_sel_hi:[1,0]
	v_pk_mul_f32 v[130:131], v[70:71], v[186:187] op_sel_hi:[1,0]
	v_pk_mul_f32 v[132:133], v[64:65], v[186:187] op_sel_hi:[1,0]
	v_pk_mul_f32 v[134:135], v[66:67], v[186:187] op_sel_hi:[1,0]
	v_pk_mul_f32 v[136:137], v[128:129], v[188:189] op_sel_hi:[1,0]
	v_pk_mul_f32 v[138:139], v[130:131], v[188:189] op_sel_hi:[1,0]
	v_pk_mul_f32 v[140:141], v[132:133], v[188:189] op_sel_hi:[1,0]
	v_pk_mul_f32 v[142:143], v[134:135], v[188:189] op_sel_hi:[1,0]
	v_exp_f32_e32 v136, v136
	v_exp_f32_e32 v137, v137
	v_exp_f32_e32 v138, v138
	v_exp_f32_e32 v139, v139
	v_exp_f32_e32 v140, v140
	v_exp_f32_e32 v141, v141
	v_exp_f32_e32 v142, v142
	v_exp_f32_e32 v143, v143
	v_pk_add_f32 v[136:137], v[136:137], 1.0 op_sel_hi:[1,0]
	v_pk_add_f32 v[138:139], v[138:139], 1.0 op_sel_hi:[1,0]
	v_pk_add_f32 v[140:141], v[140:141], 1.0 op_sel_hi:[1,0]
	v_pk_add_f32 v[142:143], v[142:143], 1.0 op_sel_hi:[1,0]
	v_rcp_f32_e32 v136, v136
	v_rcp_f32_e32 v137, v137
	v_rcp_f32_e32 v138, v138
	v_rcp_f32_e32 v139, v139
	v_rcp_f32_e32 v140, v140
	v_rcp_f32_e32 v141, v141
	v_rcp_f32_e32 v142, v142
	v_rcp_f32_e32 v143, v143
	v_pk_mul_f32 v[136:137], v[128:129], v[136:137]
	v_pk_mul_f32 v[138:139], v[130:131], v[138:139]
	v_pk_mul_f32 v[140:141], v[132:133], v[140:141]
	v_pk_mul_f32 v[142:143], v[134:135], v[142:143]
	v_cvt_pk_bf16_f32 v148, v136, v137
	v_cvt_pk_bf16_f32 v149, v138, v139
	v_cvt_pk_bf16_f32 v150, v140, v141
	v_cvt_pk_bf16_f32 v151, v142, v143
	global_store_dwordx4 v183, v[148:151], s[44:45] offset:256
